# v26 plus MLA item prologue: tile-0 rotary-key rows loaded together with the other first-tile loads instead of a second serialized round trip
# baseline (speedup 1.0000x reference)
; __device__ __forceinline__ int v_st_ns(int k, int c) { return ((k >> 3) * 2 + (c >> 5)) * 512 + ((k & 7) * 32 + (c & 31)) * 2; }
; __device__ __forceinline__ int v_rd_base(int lane) { return ((lane & 3) << 3) | (((lane >> 2) & 3) << 6) | (((lane >> 4) & 1) << 5) | (((lane >> 5) & 1) << 8); }
; #define SLOAD(i, k0) do { st_[i].vs = *reinterpret_cast<const bf16x8*>(&Vh[(size_t)((k0) + sr) * LDK + sc]); \
;     st_[i].ks = *reinterpret_cast<const bf16x8*>(&Kh[(size_t)((k0) + sr) * LDK + sc]); \
;     if (DQ == 96) st_[i].kr = *reinterpret_cast<const bf16x8*>(&Kr[(size_t)((k0) + sr2) * 32 + sc2]); } while (0)
; #define SWRITE(b, i) do { *(bf16x8*)(V_lds + (b) * SHM_V + vst0) = st_[i].vs; *(bf16x8*)(K_lds + (b) * SHM_K + kst0) = st_[i].ks; \
;     if (DQ == 96) { if (tid < 256) *(bf16x8*)(K_lds + (b) * SHM_K + kst2) = st_[i].kr; } } while (0)
; #define SWAIT() do { if (DQ == 96) asm volatile("s_waitcnt vmcnt(3)" ::: "memory"); else asm volatile("s_waitcnt vmcnt(2)" ::: "memory"); } while (0)
; template <int DQ, bool WIN, int LDQ, int LDK> ...
;     ...
;     const bf16_t* Qw = Qb + (size_t)(wid * 32 + r32) * LDQ + hi * 8;
; #pragma unroll
;     for (int d0 = 0; d0 < ND; ++d0) qr[d0] = *reinterpret_cast<const bf16x8*>(Qw + d0 * 16);
;     const int sr = tid >> 3, sc = (tid & 7) * 8, vst0 = v_st_ns(sr, sc);
;     const int kst0 = sr * KROW + sc * 2;
;     const int sr2 = (tid & 255) >> 2, sc2 = (tid & 3) * 8; const int kst2 = sr2 * KROW + 128 + sc2 * 2;
;     const int vb0 = (int)(uintptr_t)V_lds + v_rd_base(lane);
;     const int qrow = q0 + wid * 32 + r32;
;     struct { bf16x8 vs, ks, kr; } st_[2];
;     ...
;     f32x16 pA0, pA1, pB0, pB1; bf16x8 pa0, pa1, pa2, pa3;
;     auto finish = [&](f32x16& p0, f32x16& p1) {
;         exp16(p1);
;         pack_p_ns(p0, p1, pa0, pa1, pa2, pa3);
;     };
;     auto pv = [&](int vb) {
;         pv_d0(o, vb, pa0, pa1, pa2, pa3);
;     };
;     auto lsum_upd = [&]() {
;         lsum = __builtin_amdgcn_mfma_f32_32x32x16_bf16(pa0, ones8, lsum, 0, 0, 0);
;         lsum = __builtin_amdgcn_mfma_f32_32x32x16_bf16(pa1, ones8, lsum, 0, 0, 0);
;         lsum = __builtin_amdgcn_mfma_f32_32x32x16_bf16(pa2, ones8, lsum, 0, 0, 0);
;         lsum = __builtin_amdgcn_mfma_f32_32x32x16_bf16(pa3, ones8, lsum, 0, 0, 0);
;     };
;     constexpr int SE = 0, SO = 1;
;     SLOAD(SE, KBASE(0)); SLOAD(SO, KBASE(1));
;     SWAIT(); SWRITE(0, SE); __syncthreads();
.LBB0_1086:
	s_or_b64 exec, exec, s[0:1]
	s_ashr_i32 s8, s20, 9
	s_ashr_i32 s9, s8, 31
	s_lshl_b32 s0, s20, 8
	s_lshl_b64 s[14:15], s[8:9], 13
	s_and_b32 s0, s0, 0x1f00
	s_or_b32 s14, s14, s0
	s_mul_i32 s0, s15, 0xc00
	s_mul_hi_u32 s1, s14, 0xc00
	s_bfe_u32 s22, s20, 0x40005
	s_add_i32 s1, s1, s0
	s_mul_i32 s0, s14, 0xc00
	v_readlane_b32 s6, v252, 52
	v_readlane_b32 s7, v252, 53
	s_add_u32 s0, s6, s0
	s_addc_u32 s1, s7, s1
	s_mul_i32 s5, s22, 0xc0
	s_add_u32 s12, s0, s5
	s_addc_u32 s13, s1, 0
	s_lshl_b64 s[0:1], s[8:9], 25
	v_readlane_b32 s6, v254, 16
	v_readlane_b32 s7, v254, 17
	s_add_u32 s5, s6, s0
	s_addc_u32 s7, s7, s1
	s_lshl_b32 s6, s22, 8
	s_add_u32 s6, s5, s6
	s_addc_u32 s7, s7, 0
	s_lshl_b64 s[10:11], s[8:9], 19
	v_readlane_b32 s8, v254, 9
	v_readlane_b32 s9, v254, 10
	s_add_u32 s8, s8, s10
	s_addc_u32 s9, s9, s11
	s_ashr_i32 s18, s4, 1
	v_mov_b32_e32 v0, s18
	s_movk_i32 s4, 0xffe0
	v_bfe_u32 v187, v80, 5, 1
	v_bfi_b32 v2, s4, v0, v80
	v_mov_b64_e32 v[0:1], s[12:13]
	s_movk_i32 s4, 0xc00
	v_mad_i64_i32 v[0:1], s[4:5], v2, s4, v[0:1]
	v_lshlrev_b32_e32 v112, 4, v187
	v_lshl_add_u64 v[0:1], v[0:1], 0, v[112:113]
	global_load_dwordx4 v[134:137], v[0:1], off
	global_load_dwordx4 v[130:133], v[0:1], off offset:32
	global_load_dwordx4 v[126:129], v[0:1], off offset:64
	global_load_dwordx4 v[122:125], v[0:1], off offset:96
	global_load_dwordx4 v[118:121], v[0:1], off offset:128
	global_load_dwordx4 v[114:117], v[0:1], off offset:160
	v_lshlrev_b32_e32 v1, 3, v80
	v_ashrrev_i32_e32 v0, 3, v80
	v_lshrrev_b32_e32 v2, 5, v80
	v_bfe_u32 v3, v1, 5, 1
	s_mov_b32 s4, 0x7ffffe
	v_and_or_b32 v2, v2, s4, v3
	v_lshlrev_b32_e32 v3, 5, v0
	v_and_b32_e32 v81, 24, v1
	s_movk_i32 s4, 0xe0
	v_and_b32_e32 v50, 56, v1
	v_and_or_b32 v1, v3, s4, v81
	v_lshlrev_b32_e32 v1, 1, v1
	v_lshl_or_b32 v14, v2, 9, v1
	v_lshlrev_b32_e32 v2, 1, v50
	s_movk_i32 s4, 0xd0
	v_mad_u64_u32 v[8:9], s[4:5], v0, s4, v[2:3]
	v_bfe_u32 v9, v80, 2, 6
	v_ashrrev_i32_e32 v1, 31, v0
	v_lshlrev_b64 v[44:45], 12, v[0:1]
	v_lshlrev_b32_e32 v82, 5, v9
	v_mul_u32_u24_e32 v48, 0xd0, v9
	v_or_b32_e32 v0, v44, v2
	v_mov_b32_e32 v1, v45
	v_or_b32_e32 v9, v82, v81
	v_lshl_add_u64 v[10:11], s[6:7], 0, v[0:1]
	v_lshlrev_b32_e32 v12, 1, v9
	v_mov_b32_e32 v13, v113
	s_mov_b64 s[4:5], 0x40000
	global_load_dwordx4 v[0:3], v[10:11], off offset:128
	global_load_dwordx4 v[4:7], v[10:11], off
	v_lshl_add_u64 v[46:47], s[8:9], 0, v[12:13]
	v_lshl_add_u64 v[12:13], v[10:11], 0, s[4:5]
	v_add_co_u32_e32 v10, vcc, 0x40000, v10
	global_load_dwordx4 v[36:39], v[12:13], off offset:128
	s_nop 0
	v_addc_co_u32_e32 v11, vcc, 0, v11, vcc
	global_load_dwordx4 v[40:43], v[10:11], off
	v_add_co_u32_e32 v10, vcc, 0x1000, v46
	s_movk_i32 s4, 0xff
	s_nop 0
	v_addc_co_u32_e32 v11, vcc, 0, v47, vcc
	global_load_dwordx4 v[32:35], v[10:11], off
	global_load_dwordx4 v[52:55], v[46:47], off
	s_waitcnt vmcnt(3)
	s_movk_i32 s16, 0x100
	v_lshlrev_b32_e32 v49, 1, v81
	v_add_u32_e32 v192, 0, v14
	v_add_u32_e32 v193, 0, v8
	v_cmp_lt_i32_e64 s[4:5], s4, v80
	v_cmp_gt_i32_e64 s[40:41], s16, v80
	s_waitcnt vmcnt(0)
	ds_write_b128 v192, v[0:3]
	ds_write_b128 v193, v[4:7] offset:16384
	s_and_saveexec_b64 s[16:17], s[40:41]
	s_cbranch_execz .LBB0_1088
	v_add3_u32 v4, v48, v49, 0
	ds_write_b128 v4, v[52:55] offset:16512
